# S1 and S5 context-row tiles: double-buffered batched fragment loads
# speedup vs baseline: 1.0018x; 1.0018x over previous
; #define LAS __attribute__((address_space(3)))
; DEV unsigned pk2(float lo, float hi) { unsigned r; asm("v_cvt_pk_bf16_f32 %0, %1, %2" : "=v"(r) : "v"(lo), "v"(hi)); return r; }
; template <int CH>
; DEV void cg_chunk(f32x4 (&acc)[4][4], const bf16_t* ap, const bf16_t* bp, const int (&brow)[4], int K) {
;     bf16x8 a[CH][4], b[CH][4];
; #pragma unroll
;     for (int c = 0; c < CH; ++c)
; #pragma unroll
;         for (int i = 0; i < 4; ++i) { a[c][i] = *(const bf16x8*)(ap + (size_t)(16 * i) * K + 32 * c); b[c][i] = *(const bf16x8*)(bp + (size_t)brow[i] * K + 32 * c); }
; #pragma unroll
;     for (int c = 0; c < CH; ++c)
; #pragma unroll
;         for (int mi = 0; mi < 4; ++mi)
; #pragma unroll
;             for (int ni = 0; ni < 4; ++ni) acc[mi][ni] = __builtin_amdgcn_mfma_f32_16x16x32_bf16(b[c][ni], a[c][mi], acc[mi][ni], 0, 0, 0);
; }
; template <int MODE>
; DEV void cgemm_tile(const Fr& F, const bf16_t* A, const bf16_t* Bt, int K, int rb, int cb, bf16_t* O, int ldc) {
;     ...
; #pragma unroll
;     for (int mi = 0; mi < 4; ++mi)
; #pragma unroll
;         for (int ni = 0; ni < 4; ++ni) *(LAS f32x4*)(part + (w * 64 + 16 * mi + fr) * 64 + ((16 * ni + 4 * fq) ^ (fr << 2))) = acc[mi][ni];
;     __syncthreads();
;     { const int row = F.tid >> 3, c8 = (F.tid & 7) * 8, sw = (row & 15) << 2;
;       if (MODE == 0) {
;           f32x4 s0 = (f32x4){0.f, 0.f, 0.f, 0.f}, s1 = s0;
; #pragma unroll
;           for (int ww = 0; ww < 8; ++ww) { s0 += *(const LAS f32x4*)(part + (ww * 64 + row) * 64 + (c8 ^ sw)); s1 += *(const LAS f32x4*)(part + (ww * 64 + row) * 64 + ((c8 + 4) ^ sw)); }
;           u32x4 o; o.x = pk2(s0[0], s0[1]); o.y = pk2(s0[2], s0[3]); o.z = pk2(s1[0], s1[1]); o.w = pk2(s1[2], s1[3]);
;           *(u32x4*)(O + (size_t)(arow0 + row) * ldc + cb * 64 + c8) = o;
.LBB0_247:
	s_add_i32 s8, s0, 16
	s_add_i32 s16, s0, 32
	s_add_i32 s18, s0, 48
	s_ashr_i32 s1, s0, 31
	s_ashr_i32 s9, s8, 31
	s_ashr_i32 s17, s16, 31
	s_ashr_i32 s19, s18, 31
	s_lshl_b64 s[20:21], s[0:1], 11
	s_lshl_b64 s[8:9], s[8:9], 11
	s_lshl_b64 s[16:17], s[16:17], 11
	s_lshl_b64 s[18:19], s[18:19], 11
	v_lshl_add_u64 v[42:43], v[8:9], 0, s[20:21]
	v_lshl_add_u64 v[40:41], v[8:9], 0, s[8:9]
	v_lshl_add_u64 v[38:39], v[8:9], 0, s[16:17]
	v_lshl_add_u64 v[36:37], v[8:9], 0, s[18:19]
	s_add_i32 s4, s4, 32
	global_load_dwordx4 v[120:123], v[42:43], off
	global_load_dwordx4 v[124:127], v[40:41], off
	global_load_dwordx4 v[128:131], v[38:39], off
	global_load_dwordx4 v[132:135], v[36:37], off
	global_load_dwordx4 v[136:139], v[6:7], off
	global_load_dwordx4 v[152:155], v[10:11], off
	global_load_dwordx4 v[16:19], v[12:13], off
	global_load_dwordx4 v[20:23], v[14:15], off
	global_load_dwordx4 v[24:27], v[42:43], off offset:64
	global_load_dwordx4 v[28:31], v[40:41], off offset:64
	global_load_dwordx4 v[200:203], v[38:39], off offset:64
	global_load_dwordx4 v[204:207], v[36:37], off offset:64
	global_load_dwordx4 v[208:211], v[6:7], off offset:64
	global_load_dwordx4 v[212:215], v[10:11], off offset:64
	global_load_dwordx4 v[216:219], v[12:13], off offset:64
	global_load_dwordx4 v[220:223], v[14:15], off offset:64
	s_waitcnt vmcnt(8)
	v_mfma_f32_16x16x32_bf16 v[2:5], v[120:123], v[136:139], 0
	v_mfma_f32_16x16x32_bf16 v[58:61], v[124:127], v[136:139], 0
	v_mfma_f32_16x16x32_bf16 v[62:65], v[128:131], v[136:139], 0
	v_mfma_f32_16x16x32_bf16 v[68:71], v[132:135], v[136:139], 0
	v_mfma_f32_16x16x32_bf16 v[72:75], v[120:123], v[152:155], 0
	v_mfma_f32_16x16x32_bf16 v[76:79], v[124:127], v[152:155], 0
	v_mfma_f32_16x16x32_bf16 v[80:83], v[128:131], v[152:155], 0
	v_mfma_f32_16x16x32_bf16 v[84:87], v[132:135], v[152:155], 0
	v_mfma_f32_16x16x32_bf16 v[88:91], v[120:123], v[16:19], 0
	v_mfma_f32_16x16x32_bf16 v[92:95], v[124:127], v[16:19], 0
	v_mfma_f32_16x16x32_bf16 v[96:99], v[128:131], v[16:19], 0
	v_mfma_f32_16x16x32_bf16 v[100:103], v[132:135], v[16:19], 0
	v_mfma_f32_16x16x32_bf16 v[104:107], v[120:123], v[20:23], 0
	v_mfma_f32_16x16x32_bf16 v[108:111], v[124:127], v[20:23], 0
	v_mfma_f32_16x16x32_bf16 v[112:115], v[128:131], v[20:23], 0
	v_mfma_f32_16x16x32_bf16 v[116:119], v[132:135], v[20:23], 0
	global_load_dwordx4 v[120:123], v[42:43], off offset:128
	global_load_dwordx4 v[124:127], v[40:41], off offset:128
	global_load_dwordx4 v[128:131], v[38:39], off offset:128
	global_load_dwordx4 v[132:135], v[36:37], off offset:128
	global_load_dwordx4 v[136:139], v[6:7], off offset:128
	global_load_dwordx4 v[152:155], v[10:11], off offset:128
	global_load_dwordx4 v[16:19], v[12:13], off offset:128
	global_load_dwordx4 v[20:23], v[14:15], off offset:128
	s_waitcnt vmcnt(8)
	v_mfma_f32_16x16x32_bf16 v[2:5], v[24:27], v[208:211], v[2:5]
	v_mfma_f32_16x16x32_bf16 v[58:61], v[28:31], v[208:211], v[58:61]
	v_mfma_f32_16x16x32_bf16 v[62:65], v[200:203], v[208:211], v[62:65]
	v_mfma_f32_16x16x32_bf16 v[68:71], v[204:207], v[208:211], v[68:71]
	v_mfma_f32_16x16x32_bf16 v[72:75], v[24:27], v[212:215], v[72:75]
	v_mfma_f32_16x16x32_bf16 v[76:79], v[28:31], v[212:215], v[76:79]
	v_mfma_f32_16x16x32_bf16 v[80:83], v[200:203], v[212:215], v[80:83]
	v_mfma_f32_16x16x32_bf16 v[84:87], v[204:207], v[212:215], v[84:87]
	v_mfma_f32_16x16x32_bf16 v[88:91], v[24:27], v[216:219], v[88:91]
	v_mfma_f32_16x16x32_bf16 v[92:95], v[28:31], v[216:219], v[92:95]
	v_mfma_f32_16x16x32_bf16 v[96:99], v[200:203], v[216:219], v[96:99]
	v_mfma_f32_16x16x32_bf16 v[100:103], v[204:207], v[216:219], v[100:103]
	v_mfma_f32_16x16x32_bf16 v[104:107], v[24:27], v[220:223], v[104:107]
	v_mfma_f32_16x16x32_bf16 v[108:111], v[28:31], v[220:223], v[108:111]
	v_mfma_f32_16x16x32_bf16 v[112:115], v[200:203], v[220:223], v[112:115]
	v_mfma_f32_16x16x32_bf16 v[116:119], v[204:207], v[220:223], v[116:119]
	global_load_dwordx4 v[24:27], v[42:43], off offset:192
	global_load_dwordx4 v[28:31], v[40:41], off offset:192
	global_load_dwordx4 v[200:203], v[38:39], off offset:192
	global_load_dwordx4 v[204:207], v[36:37], off offset:192
	global_load_dwordx4 v[208:211], v[6:7], off offset:192
	global_load_dwordx4 v[212:215], v[10:11], off offset:192
	global_load_dwordx4 v[216:219], v[12:13], off offset:192
	global_load_dwordx4 v[220:223], v[14:15], off offset:192
	s_waitcnt vmcnt(8)
; #define LAS __attribute__((address_space(3)))
; DEV unsigned pk2(float lo, float hi) { unsigned r; asm("v_cvt_pk_bf16_f32 %0, %1, %2" : "=v"(r) : "v"(lo), "v"(hi)); return r; }
; template <int CH>
; DEV void cg_chunk(f32x4 (&acc)[4][4], const bf16_t* ap, const bf16_t* bp, const int (&brow)[4], int K) {
;     bf16x8 a[CH][4], b[CH][4];
; #pragma unroll
;     for (int c = 0; c < CH; ++c)
; #pragma unroll
;         for (int i = 0; i < 4; ++i) { a[c][i] = *(const bf16x8*)(ap + (size_t)(16 * i) * K + 32 * c); b[c][i] = *(const bf16x8*)(bp + (size_t)brow[i] * K + 32 * c); }
; #pragma unroll
;     for (int c = 0; c < CH; ++c)
; #pragma unroll
;         for (int mi = 0; mi < 4; ++mi)
; #pragma unroll
;             for (int ni = 0; ni < 4; ++ni) acc[mi][ni] = __builtin_amdgcn_mfma_f32_16x16x32_bf16(b[c][ni], a[c][mi], acc[mi][ni], 0, 0, 0);
; }
; template <int MODE>
; DEV void cgemm_tile(const Fr& F, const bf16_t* A, const bf16_t* Bt, int K, int rb, int cb, bf16_t* O, int ldc) {
;     ...
; #pragma unroll
;     for (int mi = 0; mi < 4; ++mi)
; #pragma unroll
;         for (int ni = 0; ni < 4; ++ni) *(LAS f32x4*)(part + (w * 64 + 16 * mi + fr) * 64 + ((16 * ni + 4 * fq) ^ (fr << 2))) = acc[mi][ni];
;     __syncthreads();
;     { const int row = F.tid >> 3, c8 = (F.tid & 7) * 8, sw = (row & 15) << 2;
;       if (MODE == 0) {
;           f32x4 s0 = (f32x4){0.f, 0.f, 0.f, 0.f}, s1 = s0;
; #pragma unroll
;           for (int ww = 0; ww < 8; ++ww) { s0 += *(const LAS f32x4*)(part + (ww * 64 + row) * 64 + (c8 ^ sw)); s1 += *(const LAS f32x4*)(part + (ww * 64 + row) * 64 + ((c8 + 4) ^ sw)); }
;           u32x4 o; o.x = pk2(s0[0], s0[1]); o.y = pk2(s0[2], s0[3]); o.z = pk2(s1[0], s1[1]); o.w = pk2(s1[2], s1[3]);
;           *(u32x4*)(O + (size_t)(arow0 + row) * ldc + cb * 64 + c8) = o;
	v_mfma_f32_16x16x32_bf16 v[2:5], v[120:123], v[136:139], v[2:5]
	v_mfma_f32_16x16x32_bf16 v[58:61], v[124:127], v[136:139], v[58:61]
	v_mfma_f32_16x16x32_bf16 v[62:65], v[128:131], v[136:139], v[62:65]
	v_mfma_f32_16x16x32_bf16 v[68:71], v[132:135], v[136:139], v[68:71]
	v_mfma_f32_16x16x32_bf16 v[72:75], v[120:123], v[152:155], v[72:75]
	v_mfma_f32_16x16x32_bf16 v[76:79], v[124:127], v[152:155], v[76:79]
	v_mfma_f32_16x16x32_bf16 v[80:83], v[128:131], v[152:155], v[80:83]
	v_mfma_f32_16x16x32_bf16 v[84:87], v[132:135], v[152:155], v[84:87]
	v_mfma_f32_16x16x32_bf16 v[88:91], v[120:123], v[16:19], v[88:91]
	v_mfma_f32_16x16x32_bf16 v[92:95], v[124:127], v[16:19], v[92:95]
	v_mfma_f32_16x16x32_bf16 v[96:99], v[128:131], v[16:19], v[96:99]
	v_mfma_f32_16x16x32_bf16 v[100:103], v[132:135], v[16:19], v[100:103]
	v_mfma_f32_16x16x32_bf16 v[104:107], v[120:123], v[20:23], v[104:107]
	v_mfma_f32_16x16x32_bf16 v[108:111], v[124:127], v[20:23], v[108:111]
	v_mfma_f32_16x16x32_bf16 v[112:115], v[128:131], v[20:23], v[112:115]
	v_mfma_f32_16x16x32_bf16 v[116:119], v[132:135], v[20:23], v[116:119]
	s_waitcnt vmcnt(0)
	v_mfma_f32_16x16x32_bf16 v[2:5], v[24:27], v[208:211], v[2:5]
	v_mfma_f32_16x16x32_bf16 v[58:61], v[28:31], v[208:211], v[58:61]
	v_mfma_f32_16x16x32_bf16 v[62:65], v[200:203], v[208:211], v[62:65]
	v_mfma_f32_16x16x32_bf16 v[68:71], v[204:207], v[208:211], v[68:71]
	v_mfma_f32_16x16x32_bf16 v[72:75], v[24:27], v[212:215], v[72:75]
	v_mfma_f32_16x16x32_bf16 v[76:79], v[28:31], v[212:215], v[76:79]
	v_mfma_f32_16x16x32_bf16 v[80:83], v[200:203], v[212:215], v[80:83]
	v_mfma_f32_16x16x32_bf16 v[84:87], v[204:207], v[212:215], v[84:87]
	v_mfma_f32_16x16x32_bf16 v[88:91], v[24:27], v[216:219], v[88:91]
	v_mfma_f32_16x16x32_bf16 v[92:95], v[28:31], v[216:219], v[92:95]
	v_mfma_f32_16x16x32_bf16 v[96:99], v[200:203], v[216:219], v[96:99]
	v_mfma_f32_16x16x32_bf16 v[100:103], v[204:207], v[216:219], v[100:103]
	v_mfma_f32_16x16x32_bf16 v[104:107], v[24:27], v[220:223], v[104:107]
	v_mfma_f32_16x16x32_bf16 v[108:111], v[28:31], v[220:223], v[108:111]
	v_mfma_f32_16x16x32_bf16 v[112:115], v[200:203], v[220:223], v[112:115]
	v_mfma_f32_16x16x32_bf16 v[116:119], v[204:207], v[220:223], v[116:119]
	ds_write_b128 v44, v[2:5]
	ds_write_b128 v45, v[58:61]
	ds_write_b128 v46, v[62:65]
	ds_write_b128 v47, v[68:71]
	ds_write_b128 v44, v[72:75] offset:4096
	ds_write_b128 v45, v[76:79] offset:4096
	ds_write_b128 v46, v[80:83] offset:4096
	ds_write_b128 v47, v[84:87] offset:4096
	ds_write_b128 v44, v[88:91] offset:8192
	ds_write_b128 v45, v[92:95] offset:8192
	ds_write_b128 v46, v[96:99] offset:8192
	ds_write_b128 v47, v[100:103] offset:8192
	ds_write_b128 v44, v[104:107] offset:12288
	ds_write_b128 v45, v[108:111] offset:12288
	ds_write_b128 v46, v[112:115] offset:12288
	ds_write_b128 v47, v[116:119] offset:12288
	s_waitcnt lgkmcnt(0)
	s_barrier
	ds_read_b128 v[2:5], v48
	ds_read_b128 v[36:39], v48 offset:16384
	ds_read_b128 v[40:43], v49
	ds_read_b128 v[58:61], v49 offset:16384
	ds_read_b128 v[62:65], v48 offset:32768
	ds_read_b128 v[68:71], v48 offset:49152
	ds_read_b128 v[72:75], v49 offset:32768
	ds_read_b128 v[76:79], v49 offset:49152
	ds_read_b128 v[80:83], v50
	ds_read_b128 v[84:87], v51
	ds_read_b128 v[88:91], v52
	ds_read_b128 v[92:95], v53
	ds_read_b128 v[96:99], v54
	ds_read_b128 v[100:103], v55
	ds_read_b128 v[104:107], v56
	ds_read_b128 v[108:111], v57
	s_waitcnt lgkmcnt(14)
	v_pk_add_f32 v[4:5], v[4:5], 0 op_sel_hi:[1,0]
	v_pk_add_f32 v[2:3], v[2:3], 0 op_sel_hi:[1,0]
	s_waitcnt lgkmcnt(13)
	v_pk_add_f32 v[42:43], v[42:43], 0 op_sel_hi:[1,0]
	v_pk_add_f32 v[40:41], v[40:41], 0 op_sel_hi:[1,0]
	v_pk_add_f32 v[4:5], v[4:5], v[38:39]
	v_pk_add_f32 v[2:3], v[2:3], v[36:37]
	s_waitcnt lgkmcnt(12)
	v_pk_add_f32 v[36:37], v[42:43], v[60:61]
	v_pk_add_f32 v[38:39], v[40:41], v[58:59]
	s_waitcnt lgkmcnt(11)
	v_pk_add_f32 v[4:5], v[4:5], v[64:65]
	v_pk_add_f32 v[2:3], v[2:3], v[62:63]
	s_waitcnt lgkmcnt(9)
	v_pk_add_f32 v[36:37], v[36:37], v[74:75]
	v_pk_add_f32 v[38:39], v[38:39], v[72:73]
	v_pk_add_f32 v[4:5], v[4:5], v[70:71]
	v_pk_add_f32 v[2:3], v[2:3], v[68:69]
	s_waitcnt lgkmcnt(8)
	v_pk_add_f32 v[36:37], v[36:37], v[78:79]
	v_pk_add_f32 v[38:39], v[38:39], v[76:77]
	s_waitcnt lgkmcnt(7)
	v_pk_add_f32 v[4:5], v[4:5], v[82:83]
	v_pk_add_f32 v[2:3], v[2:3], v[80:81]
	s_waitcnt lgkmcnt(6)
	v_pk_add_f32 v[36:37], v[36:37], v[86:87]
	v_pk_add_f32 v[38:39], v[38:39], v[84:85]
	s_waitcnt lgkmcnt(5)
	v_pk_add_f32 v[4:5], v[4:5], v[90:91]
	v_pk_add_f32 v[2:3], v[2:3], v[88:89]
	v_lshl_add_u64 v[120:121], s[0:1], 1, v[34:35]
	s_addk_i32 s0, 0x800
	s_waitcnt lgkmcnt(4)
	v_pk_add_f32 v[36:37], v[36:37], v[94:95]
	v_pk_add_f32 v[38:39], v[38:39], v[92:93]
	s_waitcnt lgkmcnt(3)
	v_pk_add_f32 v[4:5], v[4:5], v[98:99]
	v_pk_add_f32 v[2:3], v[2:3], v[96:97]
	s_cmp_gt_i32 s4, 4
	s_waitcnt lgkmcnt(2)
	v_pk_add_f32 v[36:37], v[36:37], v[102:103]
	v_pk_add_f32 v[38:39], v[38:39], v[100:101]
	s_waitcnt lgkmcnt(1)
	v_pk_add_f32 v[4:5], v[4:5], v[106:107]
	v_pk_add_f32 v[2:3], v[2:3], v[104:105]
	s_waitcnt lgkmcnt(0)
	v_pk_add_f32 v[36:37], v[36:37], v[110:111]
	v_pk_add_f32 v[38:39], v[38:39], v[108:109]
	v_cvt_pk_bf16_f32 v2, v2, v3
	v_cvt_pk_bf16_f32 v3, v4, v5
	v_cvt_pk_bf16_f32 v5, v36, v37
	s_nop 0
	v_cvt_pk_bf16_f32 v4, v38, v39
	global_store_dwordx4 v[120:121], v[2:5], off
	s_barrier
	s_cbranch_scc0 .LBB0_247

; #define LAS __attribute__((address_space(3)))
; DEV unsigned pk2(float lo, float hi) { unsigned r; asm("v_cvt_pk_bf16_f32 %0, %1, %2" : "=v"(r) : "v"(lo), "v"(hi)); return r; }
; template <int CH>
; DEV void cg_chunk(f32x4 (&acc)[4][4], const bf16_t* ap, const bf16_t* bp, const int (&brow)[4], int K) {
;     bf16x8 a[CH][4], b[CH][4];
; #pragma unroll
;     for (int c = 0; c < CH; ++c)
; #pragma unroll
;         for (int i = 0; i < 4; ++i) { a[c][i] = *(const bf16x8*)(ap + (size_t)(16 * i) * K + 32 * c); b[c][i] = *(const bf16x8*)(bp + (size_t)brow[i] * K + 32 * c); }
; #pragma unroll
;     for (int c = 0; c < CH; ++c)
; #pragma unroll
;         for (int mi = 0; mi < 4; ++mi)
; #pragma unroll
;             for (int ni = 0; ni < 4; ++ni) acc[mi][ni] = __builtin_amdgcn_mfma_f32_16x16x32_bf16(b[c][ni], a[c][mi], acc[mi][ni], 0, 0, 0);
; }
; template <int MODE>
; DEV void cgemm_tile(const Fr& F, const bf16_t* A, const bf16_t* Bt, int K, int rb, int cb, bf16_t* O, int ldc) {
;     ...
; #pragma unroll
;     for (int mi = 0; mi < 4; ++mi)
; #pragma unroll
;         for (int ni = 0; ni < 4; ++ni) *(LAS f32x4*)(part + (w * 64 + 16 * mi + fr) * 64 + ((16 * ni + 4 * fq) ^ (fr << 2))) = acc[mi][ni];
;     __syncthreads();
;     { const int row = F.tid >> 3, c8 = (F.tid & 7) * 8, sw = (row & 15) << 2;
;       if (MODE == 0) {
;           f32x4 s0 = (f32x4){0.f, 0.f, 0.f, 0.f}, s1 = s0;
; #pragma unroll
;           for (int ww = 0; ww < 8; ++ww) { s0 += *(const LAS f32x4*)(part + (ww * 64 + row) * 64 + (c8 ^ sw)); s1 += *(const LAS f32x4*)(part + (ww * 64 + row) * 64 + ((c8 + 4) ^ sw)); }
;           u32x4 o; o.x = pk2(s0[0], s0[1]); o.y = pk2(s0[2], s0[3]); o.z = pk2(s1[0], s1[1]); o.w = pk2(s1[2], s1[3]);
;           *(u32x4*)(O + (size_t)(arow0 + row) * ldc + cb * 64 + c8) = o;
.LBB0_1012:
	s_add_i32 s16, s0, 16
	s_add_i32 s18, s0, 32
	s_add_i32 s20, s0, 48
	s_ashr_i32 s1, s0, 31
	s_ashr_i32 s17, s16, 31
	s_ashr_i32 s19, s18, 31
	s_ashr_i32 s21, s20, 31
	s_lshl_b64 s[22:23], s[0:1], 11
	s_lshl_b64 s[16:17], s[16:17], 11
	s_lshl_b64 s[18:19], s[18:19], 11
	s_lshl_b64 s[20:21], s[20:21], 11
	v_lshl_add_u64 v[42:43], v[8:9], 0, s[22:23]
	v_lshl_add_u64 v[40:41], v[8:9], 0, s[16:17]
	v_lshl_add_u64 v[38:39], v[8:9], 0, s[18:19]
	v_lshl_add_u64 v[36:37], v[8:9], 0, s[20:21]
	s_add_i32 s2, s2, 32
	global_load_dwordx4 v[120:123], v[42:43], off
	global_load_dwordx4 v[124:127], v[40:41], off
	global_load_dwordx4 v[128:131], v[38:39], off
	global_load_dwordx4 v[132:135], v[36:37], off
	global_load_dwordx4 v[136:139], v[6:7], off
	global_load_dwordx4 v[152:155], v[10:11], off
	global_load_dwordx4 v[16:19], v[12:13], off
	global_load_dwordx4 v[20:23], v[14:15], off
	global_load_dwordx4 v[24:27], v[42:43], off offset:64
	global_load_dwordx4 v[28:31], v[40:41], off offset:64
	global_load_dwordx4 v[200:203], v[38:39], off offset:64
	global_load_dwordx4 v[204:207], v[36:37], off offset:64
	global_load_dwordx4 v[208:211], v[6:7], off offset:64
	global_load_dwordx4 v[212:215], v[10:11], off offset:64
	global_load_dwordx4 v[216:219], v[12:13], off offset:64
	global_load_dwordx4 v[220:223], v[14:15], off offset:64
	s_waitcnt vmcnt(8)
	v_mfma_f32_16x16x32_bf16 v[2:5], v[120:123], v[136:139], 0
	v_mfma_f32_16x16x32_bf16 v[58:61], v[124:127], v[136:139], 0
	v_mfma_f32_16x16x32_bf16 v[62:65], v[128:131], v[136:139], 0
	v_mfma_f32_16x16x32_bf16 v[68:71], v[132:135], v[136:139], 0
	v_mfma_f32_16x16x32_bf16 v[72:75], v[120:123], v[152:155], 0
	v_mfma_f32_16x16x32_bf16 v[76:79], v[124:127], v[152:155], 0
	v_mfma_f32_16x16x32_bf16 v[80:83], v[128:131], v[152:155], 0
	v_mfma_f32_16x16x32_bf16 v[84:87], v[132:135], v[152:155], 0
	v_mfma_f32_16x16x32_bf16 v[88:91], v[120:123], v[16:19], 0
	v_mfma_f32_16x16x32_bf16 v[92:95], v[124:127], v[16:19], 0
	v_mfma_f32_16x16x32_bf16 v[96:99], v[128:131], v[16:19], 0
	v_mfma_f32_16x16x32_bf16 v[100:103], v[132:135], v[16:19], 0
	v_mfma_f32_16x16x32_bf16 v[104:107], v[120:123], v[20:23], 0
	v_mfma_f32_16x16x32_bf16 v[108:111], v[124:127], v[20:23], 0
	v_mfma_f32_16x16x32_bf16 v[112:115], v[128:131], v[20:23], 0
	v_mfma_f32_16x16x32_bf16 v[116:119], v[132:135], v[20:23], 0
	global_load_dwordx4 v[120:123], v[42:43], off offset:128
	global_load_dwordx4 v[124:127], v[40:41], off offset:128
	global_load_dwordx4 v[128:131], v[38:39], off offset:128
	global_load_dwordx4 v[132:135], v[36:37], off offset:128
	global_load_dwordx4 v[136:139], v[6:7], off offset:128
	global_load_dwordx4 v[152:155], v[10:11], off offset:128
	global_load_dwordx4 v[16:19], v[12:13], off offset:128
	global_load_dwordx4 v[20:23], v[14:15], off offset:128
	s_waitcnt vmcnt(8)
	v_mfma_f32_16x16x32_bf16 v[2:5], v[24:27], v[208:211], v[2:5]
	v_mfma_f32_16x16x32_bf16 v[58:61], v[28:31], v[208:211], v[58:61]
	v_mfma_f32_16x16x32_bf16 v[62:65], v[200:203], v[208:211], v[62:65]
	v_mfma_f32_16x16x32_bf16 v[68:71], v[204:207], v[208:211], v[68:71]
	v_mfma_f32_16x16x32_bf16 v[72:75], v[24:27], v[212:215], v[72:75]
	v_mfma_f32_16x16x32_bf16 v[76:79], v[28:31], v[212:215], v[76:79]
	v_mfma_f32_16x16x32_bf16 v[80:83], v[200:203], v[212:215], v[80:83]
	v_mfma_f32_16x16x32_bf16 v[84:87], v[204:207], v[212:215], v[84:87]
	v_mfma_f32_16x16x32_bf16 v[88:91], v[24:27], v[216:219], v[88:91]
	v_mfma_f32_16x16x32_bf16 v[92:95], v[28:31], v[216:219], v[92:95]
	v_mfma_f32_16x16x32_bf16 v[96:99], v[200:203], v[216:219], v[96:99]
	v_mfma_f32_16x16x32_bf16 v[100:103], v[204:207], v[216:219], v[100:103]
	v_mfma_f32_16x16x32_bf16 v[104:107], v[24:27], v[220:223], v[104:107]
	v_mfma_f32_16x16x32_bf16 v[108:111], v[28:31], v[220:223], v[108:111]
	v_mfma_f32_16x16x32_bf16 v[112:115], v[200:203], v[220:223], v[112:115]
	v_mfma_f32_16x16x32_bf16 v[116:119], v[204:207], v[220:223], v[116:119]
	global_load_dwordx4 v[24:27], v[42:43], off offset:192
	global_load_dwordx4 v[28:31], v[40:41], off offset:192
	global_load_dwordx4 v[200:203], v[38:39], off offset:192
	global_load_dwordx4 v[204:207], v[36:37], off offset:192
	global_load_dwordx4 v[208:211], v[6:7], off offset:192
	global_load_dwordx4 v[212:215], v[10:11], off offset:192
	global_load_dwordx4 v[216:219], v[12:13], off offset:192
	global_load_dwordx4 v[220:223], v[14:15], off offset:192
	s_waitcnt vmcnt(8)
; #define LAS __attribute__((address_space(3)))
; DEV unsigned pk2(float lo, float hi) { unsigned r; asm("v_cvt_pk_bf16_f32 %0, %1, %2" : "=v"(r) : "v"(lo), "v"(hi)); return r; }
; template <int CH>
; DEV void cg_chunk(f32x4 (&acc)[4][4], const bf16_t* ap, const bf16_t* bp, const int (&brow)[4], int K) {
;     bf16x8 a[CH][4], b[CH][4];
; #pragma unroll
;     for (int c = 0; c < CH; ++c)
; #pragma unroll
;         for (int i = 0; i < 4; ++i) { a[c][i] = *(const bf16x8*)(ap + (size_t)(16 * i) * K + 32 * c); b[c][i] = *(const bf16x8*)(bp + (size_t)brow[i] * K + 32 * c); }
; #pragma unroll
;     for (int c = 0; c < CH; ++c)
; #pragma unroll
;         for (int mi = 0; mi < 4; ++mi)
; #pragma unroll
;             for (int ni = 0; ni < 4; ++ni) acc[mi][ni] = __builtin_amdgcn_mfma_f32_16x16x32_bf16(b[c][ni], a[c][mi], acc[mi][ni], 0, 0, 0);
; }
; template <int MODE>
; DEV void cgemm_tile(const Fr& F, const bf16_t* A, const bf16_t* Bt, int K, int rb, int cb, bf16_t* O, int ldc) {
;     ...
; #pragma unroll
;     for (int mi = 0; mi < 4; ++mi)
; #pragma unroll
;         for (int ni = 0; ni < 4; ++ni) *(LAS f32x4*)(part + (w * 64 + 16 * mi + fr) * 64 + ((16 * ni + 4 * fq) ^ (fr << 2))) = acc[mi][ni];
;     __syncthreads();
;     { const int row = F.tid >> 3, c8 = (F.tid & 7) * 8, sw = (row & 15) << 2;
;       if (MODE == 0) {
;           f32x4 s0 = (f32x4){0.f, 0.f, 0.f, 0.f}, s1 = s0;
; #pragma unroll
;           for (int ww = 0; ww < 8; ++ww) { s0 += *(const LAS f32x4*)(part + (ww * 64 + row) * 64 + (c8 ^ sw)); s1 += *(const LAS f32x4*)(part + (ww * 64 + row) * 64 + ((c8 + 4) ^ sw)); }
;           u32x4 o; o.x = pk2(s0[0], s0[1]); o.y = pk2(s0[2], s0[3]); o.z = pk2(s1[0], s1[1]); o.w = pk2(s1[2], s1[3]);
;           *(u32x4*)(O + (size_t)(arow0 + row) * ldc + cb * 64 + c8) = o;
	v_mfma_f32_16x16x32_bf16 v[2:5], v[120:123], v[136:139], v[2:5]
	v_mfma_f32_16x16x32_bf16 v[58:61], v[124:127], v[136:139], v[58:61]
	v_mfma_f32_16x16x32_bf16 v[62:65], v[128:131], v[136:139], v[62:65]
	v_mfma_f32_16x16x32_bf16 v[68:71], v[132:135], v[136:139], v[68:71]
	v_mfma_f32_16x16x32_bf16 v[72:75], v[120:123], v[152:155], v[72:75]
	v_mfma_f32_16x16x32_bf16 v[76:79], v[124:127], v[152:155], v[76:79]
	v_mfma_f32_16x16x32_bf16 v[80:83], v[128:131], v[152:155], v[80:83]
	v_mfma_f32_16x16x32_bf16 v[84:87], v[132:135], v[152:155], v[84:87]
	v_mfma_f32_16x16x32_bf16 v[88:91], v[120:123], v[16:19], v[88:91]
	v_mfma_f32_16x16x32_bf16 v[92:95], v[124:127], v[16:19], v[92:95]
	v_mfma_f32_16x16x32_bf16 v[96:99], v[128:131], v[16:19], v[96:99]
	v_mfma_f32_16x16x32_bf16 v[100:103], v[132:135], v[16:19], v[100:103]
	v_mfma_f32_16x16x32_bf16 v[104:107], v[120:123], v[20:23], v[104:107]
	v_mfma_f32_16x16x32_bf16 v[108:111], v[124:127], v[20:23], v[108:111]
	v_mfma_f32_16x16x32_bf16 v[112:115], v[128:131], v[20:23], v[112:115]
	v_mfma_f32_16x16x32_bf16 v[116:119], v[132:135], v[20:23], v[116:119]
	s_waitcnt vmcnt(0)
	v_mfma_f32_16x16x32_bf16 v[2:5], v[24:27], v[208:211], v[2:5]
	v_mfma_f32_16x16x32_bf16 v[58:61], v[28:31], v[208:211], v[58:61]
	v_mfma_f32_16x16x32_bf16 v[62:65], v[200:203], v[208:211], v[62:65]
	v_mfma_f32_16x16x32_bf16 v[68:71], v[204:207], v[208:211], v[68:71]
	v_mfma_f32_16x16x32_bf16 v[72:75], v[24:27], v[212:215], v[72:75]
	v_mfma_f32_16x16x32_bf16 v[76:79], v[28:31], v[212:215], v[76:79]
	v_mfma_f32_16x16x32_bf16 v[80:83], v[200:203], v[212:215], v[80:83]
	v_mfma_f32_16x16x32_bf16 v[84:87], v[204:207], v[212:215], v[84:87]
	v_mfma_f32_16x16x32_bf16 v[88:91], v[24:27], v[216:219], v[88:91]
	v_mfma_f32_16x16x32_bf16 v[92:95], v[28:31], v[216:219], v[92:95]
	v_mfma_f32_16x16x32_bf16 v[96:99], v[200:203], v[216:219], v[96:99]
	v_mfma_f32_16x16x32_bf16 v[100:103], v[204:207], v[216:219], v[100:103]
	v_mfma_f32_16x16x32_bf16 v[104:107], v[24:27], v[220:223], v[104:107]
	v_mfma_f32_16x16x32_bf16 v[108:111], v[28:31], v[220:223], v[108:111]
	v_mfma_f32_16x16x32_bf16 v[112:115], v[200:203], v[220:223], v[112:115]
	v_mfma_f32_16x16x32_bf16 v[116:119], v[204:207], v[220:223], v[116:119]
	ds_write_b128 v44, v[2:5]
	ds_write_b128 v45, v[58:61]
	ds_write_b128 v46, v[62:65]
	ds_write_b128 v47, v[68:71]
	ds_write_b128 v44, v[72:75] offset:4096
	ds_write_b128 v45, v[76:79] offset:4096
	ds_write_b128 v46, v[80:83] offset:4096
	ds_write_b128 v47, v[84:87] offset:4096
	ds_write_b128 v44, v[88:91] offset:8192
	ds_write_b128 v45, v[92:95] offset:8192
	ds_write_b128 v46, v[96:99] offset:8192
	ds_write_b128 v47, v[100:103] offset:8192
	ds_write_b128 v44, v[104:107] offset:12288
	ds_write_b128 v45, v[108:111] offset:12288
	ds_write_b128 v46, v[112:115] offset:12288
	ds_write_b128 v47, v[116:119] offset:12288
	s_waitcnt lgkmcnt(0)
	s_barrier
	ds_read_b128 v[2:5], v48
	ds_read_b128 v[36:39], v48 offset:16384
	ds_read_b128 v[40:43], v49
	ds_read_b128 v[58:61], v49 offset:16384
	ds_read_b128 v[62:65], v48 offset:32768
	ds_read_b128 v[68:71], v48 offset:49152
	ds_read_b128 v[72:75], v49 offset:32768
	ds_read_b128 v[76:79], v49 offset:49152
	ds_read_b128 v[80:83], v50
	ds_read_b128 v[84:87], v51
	ds_read_b128 v[88:91], v52
	ds_read_b128 v[92:95], v53
	ds_read_b128 v[96:99], v54
	ds_read_b128 v[100:103], v55
	ds_read_b128 v[104:107], v56
	ds_read_b128 v[108:111], v57
	s_waitcnt lgkmcnt(14)
	v_pk_add_f32 v[4:5], v[4:5], 0 op_sel_hi:[1,0]
	v_pk_add_f32 v[2:3], v[2:3], 0 op_sel_hi:[1,0]
	s_waitcnt lgkmcnt(13)
	v_pk_add_f32 v[42:43], v[42:43], 0 op_sel_hi:[1,0]
	v_pk_add_f32 v[40:41], v[40:41], 0 op_sel_hi:[1,0]
	v_pk_add_f32 v[4:5], v[4:5], v[38:39]
	v_pk_add_f32 v[2:3], v[2:3], v[36:37]
	s_waitcnt lgkmcnt(12)
	v_pk_add_f32 v[36:37], v[42:43], v[60:61]
	v_pk_add_f32 v[38:39], v[40:41], v[58:59]
	s_waitcnt lgkmcnt(11)
	v_pk_add_f32 v[4:5], v[4:5], v[64:65]
	v_pk_add_f32 v[2:3], v[2:3], v[62:63]
	s_waitcnt lgkmcnt(9)
	v_pk_add_f32 v[36:37], v[36:37], v[74:75]
	v_pk_add_f32 v[38:39], v[38:39], v[72:73]
	v_pk_add_f32 v[4:5], v[4:5], v[70:71]
	v_pk_add_f32 v[2:3], v[2:3], v[68:69]
	s_waitcnt lgkmcnt(8)
	v_pk_add_f32 v[36:37], v[36:37], v[78:79]
	v_pk_add_f32 v[38:39], v[38:39], v[76:77]
	s_waitcnt lgkmcnt(7)
	v_pk_add_f32 v[4:5], v[4:5], v[82:83]
	v_pk_add_f32 v[2:3], v[2:3], v[80:81]
	s_waitcnt lgkmcnt(6)
	v_pk_add_f32 v[36:37], v[36:37], v[86:87]
	v_pk_add_f32 v[38:39], v[38:39], v[84:85]
	s_waitcnt lgkmcnt(5)
	v_pk_add_f32 v[4:5], v[4:5], v[90:91]
	v_pk_add_f32 v[2:3], v[2:3], v[88:89]
	v_lshl_add_u64 v[120:121], s[0:1], 1, v[34:35]
	s_addk_i32 s0, 0x800
	s_waitcnt lgkmcnt(4)
	v_pk_add_f32 v[36:37], v[36:37], v[94:95]
	v_pk_add_f32 v[38:39], v[38:39], v[92:93]
	s_waitcnt lgkmcnt(3)
	v_pk_add_f32 v[4:5], v[4:5], v[98:99]
	v_pk_add_f32 v[2:3], v[2:3], v[96:97]
	s_cmpk_gt_i32 s2, 0xffef
	s_waitcnt lgkmcnt(2)
	v_pk_add_f32 v[36:37], v[36:37], v[102:103]
	v_pk_add_f32 v[38:39], v[38:39], v[100:101]
	s_waitcnt lgkmcnt(1)
	v_pk_add_f32 v[4:5], v[4:5], v[106:107]
	v_pk_add_f32 v[2:3], v[2:3], v[104:105]
	s_waitcnt lgkmcnt(0)
	v_pk_add_f32 v[36:37], v[36:37], v[110:111]
	v_pk_add_f32 v[38:39], v[38:39], v[108:109]
	v_cvt_pk_bf16_f32 v2, v2, v3
	v_cvt_pk_bf16_f32 v3, v4, v5
	v_cvt_pk_bf16_f32 v5, v36, v37
	s_nop 0
	v_cvt_pk_bf16_f32 v4, v38, v39
	global_store_dwordx4 v[120:121], v[2:5], off
	s_barrier
	s_cbranch_scc0 .LBB0_1012
